# prompt attention P.V: 20 V ds_read2_b64 per q-tile hoisted above the pack/div VALU block into free VGPRs, counted lgkmcnt before each MFMA
# baseline (speedup 1.0000x reference)
.LBB0_559:
	v_lshlrev_b32_e32 v25, 3, v100
	v_sub_u32_e32 v100, v83, v25
	ds_bpermute_b32 v25, v69, v24
	s_add_u32 s10, s94, s76
	s_addc_u32 s11, s95, s77
	v_lshlrev_b32_e32 v174, 1, v73
	v_lshl_add_u64 v[26:27], s[10:11], 0, v[174:175]
	s_waitcnt lgkmcnt(0)
	v_add_f32_e32 v24, v24, v25
	ds_bpermute_b32 v25, v71, v24
	s_mov_b64 s[10:11], 0x4a40000
	v_lshl_add_u64 v[52:53], v[26:27], 0, s[10:11]
	s_waitcnt lgkmcnt(0)
	v_lshl_add_u32 v224, s4, 1, v100
	v_mul_u32_u24_e32 v229, 0x210, v61
	v_add_u32_e32 v224, v224, v229
	v_add_u32_e32 v225, 0x9000, v224
	v_add_u32_e32 v226, 0xb000, v224
	v_add_u32_e32 v227, 0xd000, v224
	v_add_u32_e32 v228, 0xf000, v224
	ds_read2_b64 v[130:133], v225 offset1:4
	ds_read2_b64 v[134:137], v225 offset0:8 offset1:12
	ds_read2_b64 v[138:141], v225 offset0:16 offset1:20
	ds_read2_b64 v[142:145], v225 offset0:24 offset1:28
	ds_read2_b64 v[146:149], v225 offset0:32 offset1:36
	ds_read2_b64 v[150:153], v226 offset0:32 offset1:36
	ds_read2_b64 v[154:157], v226 offset0:40 offset1:44
	ds_read2_b64 v[158:161], v226 offset0:48 offset1:52
	ds_read2_b64 v[162:165], v226 offset0:56 offset1:60
	ds_read2_b64 v[166:169], v226 offset0:64 offset1:68
	ds_read2_b64 v[184:187], v227 offset0:64 offset1:68
	ds_read2_b64 v[188:191], v227 offset0:72 offset1:76
	ds_read2_b64 v[192:195], v227 offset0:80 offset1:84
	ds_read2_b64 v[196:199], v227 offset0:88 offset1:92
	ds_read2_b64 v[200:203], v227 offset0:96 offset1:100
	ds_read2_b64 v[204:207], v228 offset0:96 offset1:100
	ds_read2_b64 v[208:211], v228 offset0:104 offset1:108
	ds_read2_b64 v[212:215], v228 offset0:112 offset1:116
	ds_read2_b64 v[216:219], v228 offset0:120 offset1:124
	ds_read2_b64 v[220:223], v228 offset0:128 offset1:132
	v_add_f32_e32 v24, v24, v25
	v_sub_f32_e32 v25, v67, v46
	v_exp_f32_e32 v25, v25
	s_nop 0
	v_add_f32_e32 v46, v25, v24
	v_cvt_pk_bf16_f32 v24, v44, v45
	v_div_scale_f32 v44, s[10:11], v46, v46, 1.0
	v_rcp_f32_e32 v45, v44
	v_cvt_pk_bf16_f32 v25, v47, v48
	v_cvt_pk_bf16_f32 v26, v49, v50
	s_lshl_b32 s10, s4, 1
	v_fma_f32 v47, -v44, v45, 1.0
	v_fmac_f32_e32 v45, v47, v45
	v_div_scale_f32 v47, vcc, 1.0, v46, 1.0
	v_mul_f32_e32 v48, v47, v45
	v_fma_f32 v49, -v44, v48, v47
	v_fmac_f32_e32 v48, v49, v45
	v_fma_f32 v44, -v44, v48, v47
	v_div_fmas_f32 v44, v44, v45, v48
	v_mul_u32_u24_e32 v45, 0x210, v61
	v_add3_u32 v45, v100, s10, v45
	v_cvt_pk_bf16_f32 v27, v51, v108
	v_cvt_pk_bf16_f32 v36, v54, v55
	v_add_u32_e32 v55, 0x9000, v45
	v_cvt_pk_bf16_f32 v37, v56, v57
	v_cvt_pk_bf16_f32 v38, v58, v59
	v_cvt_pk_bf16_f32 v39, v109, v110
	v_cvt_pk_bf16_f32 v32, v28, v29
	v_cvt_pk_bf16_f32 v33, v30, v31
	v_cvt_pk_bf16_f32 v34, v111, v112
	v_cvt_pk_bf16_f32 v35, v113, v35
	v_cvt_pk_bf16_f32 v28, v114, v115
	v_cvt_pk_bf16_f32 v29, v116, v117
	v_cvt_pk_bf16_f32 v30, v40, v41
	v_cvt_pk_bf16_f32 v31, v42, v118
	v_cvt_pk_bf16_f32 v40, v43, v89
	v_cvt_pk_bf16_f32 v41, v101, v103
	v_cvt_pk_bf16_f32 v42, v102, v105
	v_cvt_pk_bf16_f32 v43, v107, v106
	s_waitcnt lgkmcnt(15)
	v_mfma_f32_16x16x32_bf16 v[48:51], v[130:133], v[24:27], 0
	v_div_fixup_f32 v44, v44, v46, 1.0
	v_lshlrev_b64 v[46:47], 11, v[62:63]
	v_lshl_add_u64 v[46:47], v[52:53], 0, v[46:47]
	s_waitcnt lgkmcnt(15)
	v_mfma_f32_16x16x32_bf16 v[48:51], v[134:137], v[36:39], v[48:51]
	s_mov_b64 s[10:11], -1
	s_andn2_b64 vcc, exec, s[54:55]
	s_waitcnt lgkmcnt(15)
	v_mfma_f32_16x16x32_bf16 v[48:51], v[138:141], v[32:35], v[48:51]
	v_mul_f32_e32 v54, 0x43000000, v64
	s_waitcnt lgkmcnt(15)
	v_mfma_f32_16x16x32_bf16 v[48:51], v[142:145], v[28:31], v[48:51]
	s_waitcnt lgkmcnt(15)
	v_mfma_f32_16x16x32_bf16 v[48:51], v[146:149], v[40:43], v[48:51]
	v_add_u32_e32 v56, 0xb000, v45
	v_add_u32_e32 v57, 0xd000, v45
	v_add_u32_e32 v58, 0xf000, v45
	s_nop 4
	v_pk_mul_f32 v[48:49], v[44:45], v[48:49] op_sel_hi:[0,1]
	v_pk_mul_f32 v[50:51], v[44:45], v[50:51] op_sel_hi:[0,1]
	v_cvt_pk_bf16_f32 v48, v48, v49
	v_cvt_pk_bf16_f32 v49, v50, v51
	global_store_dwordx2 v[46:47], v[48:49], off
	s_waitcnt lgkmcnt(14)
	v_mfma_f32_16x16x32_bf16 v[48:51], v[150:153], v[24:27], 0
	v_or_b32_e32 v59, 0x90, v90
	v_sub_u32_e32 v62, v59, v87
	s_waitcnt lgkmcnt(13)
	v_mfma_f32_16x16x32_bf16 v[48:51], v[154:157], v[36:39], v[48:51]
	s_waitcnt lgkmcnt(12)
	v_mfma_f32_16x16x32_bf16 v[48:51], v[158:161], v[32:35], v[48:51]
	s_waitcnt lgkmcnt(11)
	v_mfma_f32_16x16x32_bf16 v[48:51], v[162:165], v[28:31], v[48:51]
	s_waitcnt lgkmcnt(10)
	v_mfma_f32_16x16x32_bf16 v[48:51], v[166:169], v[40:43], v[48:51]
	s_nop 7
	v_pk_mul_f32 v[48:49], v[44:45], v[48:49] op_sel_hi:[0,1]
	v_pk_mul_f32 v[50:51], v[44:45], v[50:51] op_sel_hi:[0,1]
	v_cvt_pk_bf16_f32 v48, v48, v49
	v_cvt_pk_bf16_f32 v49, v50, v51
	global_store_dwordx2 v[46:47], v[48:49], off offset:32
	s_waitcnt lgkmcnt(9)
	v_mfma_f32_16x16x32_bf16 v[48:51], v[184:187], v[24:27], 0
	s_waitcnt lgkmcnt(8)
	v_mfma_f32_16x16x32_bf16 v[48:51], v[188:191], v[36:39], v[48:51]
	s_waitcnt lgkmcnt(7)
	v_mfma_f32_16x16x32_bf16 v[48:51], v[192:195], v[32:35], v[48:51]
	s_waitcnt lgkmcnt(6)
	v_mfma_f32_16x16x32_bf16 v[48:51], v[196:199], v[28:31], v[48:51]
	s_waitcnt lgkmcnt(5)
	v_mfma_f32_16x16x32_bf16 v[48:51], v[200:203], v[40:43], v[48:51]
	s_nop 7
	v_pk_mul_f32 v[48:49], v[44:45], v[48:49] op_sel_hi:[0,1]
	v_pk_mul_f32 v[50:51], v[44:45], v[50:51] op_sel_hi:[0,1]
	v_cvt_pk_bf16_f32 v48, v48, v49
	v_cvt_pk_bf16_f32 v49, v50, v51
	global_store_dwordx2 v[46:47], v[48:49], off offset:64
	s_waitcnt lgkmcnt(4)
	v_mfma_f32_16x16x32_bf16 v[24:27], v[204:207], v[24:27], 0
	s_waitcnt lgkmcnt(3)
	v_mfma_f32_16x16x32_bf16 v[24:27], v[208:211], v[36:39], v[24:27]
	s_waitcnt lgkmcnt(2)
	v_mfma_f32_16x16x32_bf16 v[24:27], v[212:215], v[32:35], v[24:27]
	s_waitcnt lgkmcnt(1)
	v_mfma_f32_16x16x32_bf16 v[24:27], v[216:219], v[28:31], v[24:27]
	s_waitcnt lgkmcnt(0)
	v_mfma_f32_16x16x32_bf16 v[24:27], v[220:223], v[40:43], v[24:27]
	s_nop 7
	v_pk_mul_f32 v[24:25], v[44:45], v[24:25] op_sel_hi:[0,1]
	v_cvt_pk_bf16_f32 v24, v24, v25
	v_pk_mul_f32 v[26:27], v[44:45], v[26:27] op_sel_hi:[0,1]
	v_cvt_pk_bf16_f32 v25, v26, v27
	global_store_dwordx2 v[46:47], v[24:25], off offset:96
	v_cndmask_b32_e64 v24, 0, 1, s[54:55]
	v_cmp_ne_u32_e64 s[24:25], 1, v24
	s_cbranch_vccnz .LBB0_561
	v_mad_u32_u24 v44, v99, s97, v83
	v_cvt_f32_ubyte0_e32 v142, v62
	ds_read_b128 v[24:27], v44
	ds_read_b128 v[28:31], v44 offset:64
	v_mov_b32_e32 v143, v64
	v_mov_b32_e32 v178, v176
	v_pk_mul_f32 v[146:147], v[142:143], v[178:179]
	v_cmp_ge_u32_e64 s[26:27], v85, v61
	v_add_f32_e32 v145, v64, v146
	v_mov_b32_e32 v144, v146
	v_pk_add_f32 v[148:149], v[78:79], v[146:147] op_sel_hi:[1,0]
	v_pk_add_f32 v[32:33], v[144:145], v[80:81] op_sel_hi:[1,0]
	v_pk_add_f32 v[34:35], v[80:81], v[148:149] op_sel_hi:[0,1]
	v_pk_add_f32 v[46:47], v[76:77], v[148:149] op_sel_hi:[0,1]
	v_cmp_lt_u32_e32 vcc, v73, v61
	s_waitcnt vmcnt(9) lgkmcnt(1)
	v_mfma_f32_16x16x32_bf16 v[24:27], v[24:27], v[16:19], v[32:35]
	s_nop 2
	ds_read_b128 v[32:35], v44 offset:2304
	ds_read_b128 v[36:39], v44 offset:2368
	v_pk_add_f32 v[140:141], v[144:145], v[66:67] op_sel_hi:[1,0]
	s_mov_b64 s[10:11], 0
	s_waitcnt vmcnt(8) lgkmcnt(2)
	v_mfma_f32_16x16x32_bf16 v[40:43], v[28:31], v[20:23], v[24:27]
	s_nop 2
	ds_read_b128 v[24:27], v44 offset:4608
	ds_read_b128 v[28:31], v44 offset:4672
	v_pk_add_f32 v[44:45], v[144:145], v[76:77] op_sel_hi:[1,0]
	s_waitcnt lgkmcnt(3)
	s_nop 0
	v_mfma_f32_16x16x32_bf16 v[32:35], v[32:35], v[16:19], v[44:47]
	s_nop 2
	ds_read_b128 v[44:47], v98 offset:9216
	ds_read_b128 v[100:103], v98 offset:9280
	ds_read_b128 v[104:107], v98 offset:11520
	ds_read_b128 v[108:111], v98 offset:11584
	s_waitcnt lgkmcnt(6)
	v_mfma_f32_16x16x32_bf16 v[48:51], v[36:39], v[20:23], v[32:35]
	ds_read_b128 v[36:39], v98 offset:13824
	ds_read_b128 v[112:115], v98 offset:13888
	ds_read_b128 v[116:119], v98 offset:16128
	ds_read_b128 v[120:123], v98 offset:16192
	ds_read_b128 v[124:127], v98 offset:18432
	ds_read_b128 v[128:131], v98 offset:18496
	v_pk_add_f32 v[32:33], v[144:145], v[74:75] op_sel_hi:[1,0]
	v_pk_add_f32 v[34:35], v[74:75], v[148:149] op_sel_hi:[0,1]
	ds_read_b128 v[132:135], v98 offset:20736
	ds_read_b128 v[136:139], v98 offset:20800
	s_waitcnt lgkmcnt(13)
	v_mfma_f32_16x16x32_bf16 v[24:27], v[24:27], v[16:19], v[32:35]
	s_waitcnt lgkmcnt(12)
	v_mfma_f32_16x16x32_bf16 v[28:31], v[28:31], v[20:23], v[24:27]
	s_nop 0
	v_add_f32_e64 v32, v144, v70
	v_add_f32_e64 v33, v145, v70
	v_pk_add_f32 v[34:35], v[70:71], v[148:149] op_sel_hi:[0,1]
	s_nop 1
	v_pk_add_f32 v[24:25], v[144:145], v[72:73] op_sel_hi:[1,0]
	v_pk_add_f32 v[26:27], v[72:73], v[148:149] op_sel_hi:[0,1]
	s_waitcnt lgkmcnt(9)
	v_mfma_f32_16x16x32_bf16 v[32:35], v[104:107], v[16:19], v[32:35]
	v_cndmask_b32_e64 v104, v243, v41, s[26:27]
	v_cmp_ge_u32_e64 s[26:27], v77, v61
	v_cndmask_b32_e32 v106, v40, v243, vcc
	v_mfma_f32_16x16x32_bf16 v[24:27], v[44:47], v[16:19], v[24:27]
	v_cndmask_b32_e64 v107, v243, v42, s[26:27]
	v_cmp_ge_u32_e64 s[26:27], v75, v61
	v_max3_f32 v40, v67, v106, v104
	v_pk_add_f32 v[44:45], v[144:145], v[68:69] op_sel_hi:[1,0]
	v_cndmask_b32_e64 v105, v243, v43, s[26:27]
	v_pk_add_f32 v[46:47], v[68:69], v[148:149] op_sel_hi:[0,1]
	v_max3_f32 v40, v40, v107, v105
	v_mfma_f32_16x16x32_bf16 v[24:27], v[100:103], v[20:23], v[24:27]
	v_add_f32_e64 v100, v144, v54
	v_add_f32_e64 v101, v145, v54
	v_mov_b32_e32 v144, v147
	v_pk_fma_f32 v[144:145], v[142:143], v[178:179], v[144:145]
	s_waitcnt lgkmcnt(7)
	v_mfma_f32_16x16x32_bf16 v[36:39], v[36:39], v[16:19], v[44:47]
	v_add_f32_e64 v142, v66, v148
	v_add_f32_e64 v143, v66, v149
	v_pk_add_f32 v[102:103], v[54:55], v[148:149] op_sel_hi:[0,1]
	v_pk_add_f32 v[146:147], v[146:147], v[148:149] op_sel:[1,0]
	v_max3_f32 v44, v40, v48, v49
	v_max3_f32 v44, v44, v50, v51
	v_max3_f32 v44, v44, v28, v29
	v_mfma_f32_16x16x32_bf16 v[32:35], v[108:111], v[20:23], v[32:35]
	v_max3_f32 v44, v44, v30, v31
	v_max3_f32 v44, v44, v24, v25
	v_max3_f32 v89, v44, v26, v27
	s_waitcnt lgkmcnt(5)
	v_mfma_f32_16x16x32_bf16 v[40:43], v[116:119], v[16:19], v[140:143]
	v_cmp_le_u32_e64 s[26:27], v73, v61
	s_nop 1
	v_max3_f32 v89, v89, v32, v33
	v_max3_f32 v89, v89, v34, v35
	v_mfma_f32_16x16x32_bf16 v[36:39], v[112:115], v[20:23], v[36:39]
	s_waitcnt lgkmcnt(3)
	v_mfma_f32_16x16x32_bf16 v[44:47], v[124:127], v[16:19], v[100:103]
	s_waitcnt lgkmcnt(1)
	v_mfma_f32_16x16x32_bf16 v[100:103], v[132:135], v[16:19], v[144:147]
	s_nop 3
	v_max3_f32 v89, v89, v36, v37
	v_max3_f32 v89, v89, v38, v39
	v_mfma_f32_16x16x32_bf16 v[40:43], v[120:123], v[20:23], v[40:43]
	v_mfma_f32_16x16x32_bf16 v[44:47], v[128:131], v[20:23], v[44:47]
	s_waitcnt lgkmcnt(0)
	v_mfma_f32_16x16x32_bf16 v[100:103], v[136:139], v[20:23], v[100:103]
	s_nop 4
	v_max3_f32 v89, v89, v40, v41
	v_max3_f32 v89, v89, v42, v43
	v_max3_f32 v89, v89, v44, v45
	v_max3_f32 v99, v89, v46, v47
	v_cndmask_b32_e32 v89, v243, v101, vcc
	v_cmp_le_u32_e32 vcc, v77, v61
	v_cndmask_b32_e64 v100, v243, v100, s[26:27]
	v_max3_f32 v99, v99, v100, v89
	v_cndmask_b32_e32 v102, v243, v102, vcc
	v_cmp_le_u32_e32 vcc, v75, v61
	s_nop 1
	v_cndmask_b32_e32 v101, v243, v103, vcc
	v_max3_f32 v108, v99, v102, v101

.LBB0_565:
	v_sub_f32_e32 v17, v106, v16
	v_exp_f32_e32 v17, v17
	v_sub_f32_e32 v19, v104, v16
	v_exp_f32_e32 v19, v19
	s_waitcnt vmcnt(8)
	v_sub_f32_e32 v20, v107, v16
	v_exp_f32_e32 v20, v20
	v_sub_f32_e32 v21, v105, v16
	v_exp_f32_e32 v21, v21
	v_sub_f32_e32 v22, v48, v16
	v_add_f32_e32 v18, v17, v99
	v_exp_f32_e32 v22, v22
	v_sub_f32_e32 v23, v49, v16
	v_add_f32_e32 v18, v19, v18
	v_exp_f32_e32 v23, v23
	v_sub_f32_e32 v48, v50, v16
	v_add_f32_e32 v18, v20, v18
	v_exp_f32_e32 v48, v48
	v_sub_f32_e32 v49, v51, v16
	v_add_f32_e32 v18, v21, v18
	v_exp_f32_e32 v49, v49
	v_sub_f32_e32 v28, v28, v16
	v_add_f32_e32 v18, v22, v18
	v_exp_f32_e32 v50, v28
	v_sub_f32_e32 v28, v29, v16
	v_add_f32_e32 v18, v23, v18
	v_exp_f32_e32 v51, v28
	v_sub_f32_e32 v28, v30, v16
	v_add_f32_e32 v18, v48, v18
	v_exp_f32_e32 v59, v28
	v_sub_f32_e32 v28, v31, v16
	v_add_f32_e32 v18, v49, v18
	v_exp_f32_e32 v31, v28
	v_sub_f32_e32 v24, v24, v16
	v_add_f32_e32 v18, v50, v18
	v_exp_f32_e32 v24, v24
	v_sub_f32_e32 v25, v25, v16
	v_add_f32_e32 v18, v51, v18
	v_exp_f32_e32 v25, v25
	v_sub_f32_e32 v26, v26, v16
	v_add_f32_e32 v18, v59, v18
	v_exp_f32_e32 v26, v26
	v_sub_f32_e32 v27, v27, v16
	v_add_f32_e32 v18, v31, v18
	v_exp_f32_e32 v27, v27
	v_sub_f32_e32 v28, v32, v16
	v_add_f32_e32 v18, v24, v18
	v_exp_f32_e32 v62, v28
	v_sub_f32_e32 v28, v33, v16
	v_add_f32_e32 v18, v25, v18
	v_exp_f32_e32 v88, v28
	v_sub_f32_e32 v28, v34, v16
	v_add_f32_e32 v18, v26, v18
	v_exp_f32_e32 v91, v28
	v_sub_f32_e32 v28, v35, v16
	v_add_f32_e32 v18, v27, v18
	v_exp_f32_e32 v92, v28
	v_sub_f32_e32 v28, v36, v16
	v_add_f32_e32 v18, v62, v18
	v_exp_f32_e32 v36, v28
	v_sub_f32_e32 v28, v37, v16
	v_add_f32_e32 v18, v88, v18
	v_exp_f32_e32 v37, v28
	v_sub_f32_e32 v28, v38, v16
	v_add_f32_e32 v18, v91, v18
	v_exp_f32_e32 v38, v28
	v_sub_f32_e32 v28, v39, v16
	v_add_f32_e32 v18, v92, v18
	v_exp_f32_e32 v39, v28
	v_sub_f32_e32 v28, v40, v16
	v_add_f32_e32 v18, v36, v18
	v_exp_f32_e32 v40, v28
	v_sub_f32_e32 v28, v41, v16
	v_add_f32_e32 v18, v37, v18
	v_exp_f32_e32 v41, v28
	v_sub_f32_e32 v28, v42, v16
	v_add_f32_e32 v18, v38, v18
	v_exp_f32_e32 v42, v28
	v_sub_f32_e32 v28, v43, v16
	v_add_f32_e32 v18, v39, v18
	v_exp_f32_e32 v43, v28
	v_sub_f32_e32 v28, v44, v16
	v_add_f32_e32 v18, v40, v18
	v_exp_f32_e32 v44, v28
	v_sub_f32_e32 v28, v45, v16
	v_add_f32_e32 v18, v41, v18
	v_exp_f32_e32 v45, v28
	v_sub_f32_e32 v28, v46, v16
	v_add_f32_e32 v18, v42, v18
	v_exp_f32_e32 v46, v28
	v_sub_f32_e32 v28, v47, v16
	v_add_f32_e32 v18, v43, v18
	v_exp_f32_e32 v47, v28
	v_sub_f32_e32 v28, v100, v16
	v_add_f32_e32 v18, v44, v18
	v_exp_f32_e32 v93, v28
	v_sub_f32_e32 v28, v89, v16
	v_add_f32_e32 v18, v45, v18
	v_exp_f32_e32 v89, v28
	v_sub_f32_e32 v28, v102, v16
	v_add_f32_e32 v18, v46, v18
	v_exp_f32_e32 v94, v28
	v_sub_f32_e32 v28, v101, v16
	v_add_f32_e32 v18, v47, v18
	v_exp_f32_e32 v95, v28
	v_add_f32_e32 v18, v93, v18
	v_add_f32_e32 v18, v89, v18
	v_add_f32_e32 v18, v94, v18
	v_add_f32_e32 v18, v95, v18
	ds_bpermute_b32 v28, v69, v18
	v_sub_f32_e32 v16, v67, v16
	v_exp_f32_e32 v16, v16
	v_cvt_pk_bf16_f32 v32, v103, v103
	v_cvt_pk_bf16_f32 v33, v103, v103
	s_waitcnt lgkmcnt(0)
	v_add_f32_e32 v18, v18, v28
	ds_bpermute_b32 v28, v71, v18
	v_cvt_pk_bf16_f32 v34, v17, v19
	v_cvt_pk_bf16_f32 v35, v20, v21
	v_mov_b32_e32 v87, v63
	s_or_b32 s12, s4, 32
	s_waitcnt lgkmcnt(0)
	ds_read2_b64 v[130:133], v55 offset1:4
	ds_read2_b64 v[134:137], v55 offset0:8 offset1:12
	ds_read2_b64 v[138:141], v55 offset0:16 offset1:20
	ds_read2_b64 v[142:145], v55 offset0:24 offset1:28
	ds_read2_b64 v[146:149], v55 offset0:32 offset1:36
	ds_read2_b64 v[150:153], v56 offset0:32 offset1:36
	ds_read2_b64 v[154:157], v56 offset0:40 offset1:44
	ds_read2_b64 v[158:161], v56 offset0:48 offset1:52
	ds_read2_b64 v[162:165], v56 offset0:56 offset1:60
	ds_read2_b64 v[166:169], v56 offset0:64 offset1:68
	ds_read2_b64 v[184:187], v57 offset0:64 offset1:68
	ds_read2_b64 v[188:191], v57 offset0:72 offset1:76
	ds_read2_b64 v[192:195], v57 offset0:80 offset1:84
	ds_read2_b64 v[196:199], v57 offset0:88 offset1:92
	ds_read2_b64 v[200:203], v57 offset0:96 offset1:100
	ds_read2_b64 v[204:207], v58 offset0:96 offset1:100
	ds_read2_b64 v[208:211], v58 offset0:104 offset1:108
	ds_read2_b64 v[212:215], v58 offset0:112 offset1:116
	ds_read2_b64 v[216:219], v58 offset0:120 offset1:124
	ds_read2_b64 v[220:223], v58 offset0:128 offset1:132
	v_add_f32_e32 v18, v18, v28
	v_add_f32_e32 v96, v16, v18
	v_cvt_pk_bf16_f32 v28, v22, v23
	v_cvt_pk_bf16_f32 v29, v48, v49
	v_cvt_pk_bf16_f32 v30, v50, v51
	v_cvt_pk_bf16_f32 v31, v59, v31
	v_cvt_pk_bf16_f32 v24, v24, v25
	v_cvt_pk_bf16_f32 v25, v26, v27
	v_cvt_pk_bf16_f32 v26, v62, v88
	v_cvt_pk_bf16_f32 v27, v91, v92
	v_cvt_pk_bf16_f32 v20, v36, v37
	v_div_scale_f32 v36, s[10:11], v96, v96, 1.0
	v_rcp_f32_e32 v37, v36
	v_cvt_pk_bf16_f32 v21, v38, v39
	v_cvt_pk_bf16_f32 v22, v40, v41
	v_cvt_pk_bf16_f32 v23, v42, v43
	v_cvt_pk_bf16_f32 v16, v44, v45
	v_cvt_pk_bf16_f32 v17, v46, v47
	s_nop 0
	v_fma_f32 v38, -v36, v37, 1.0
	v_fmac_f32_e32 v37, v38, v37
	v_div_scale_f32 v38, vcc, 1.0, v96, 1.0
	v_mul_f32_e32 v39, v38, v37
	v_fma_f32 v40, -v36, v39, v38
	v_cvt_pk_bf16_f32 v18, v93, v89
	v_cvt_pk_bf16_f32 v19, v94, v95
	v_fmac_f32_e32 v39, v40, v37
	s_waitcnt lgkmcnt(15)
	v_mfma_f32_16x16x32_bf16 v[40:43], v[130:133], v[32:35], 0
	v_fma_f32 v36, -v36, v39, v38
	v_div_fmas_f32 v36, v36, v37, v39
	v_div_fixup_f32 v38, v36, v96, 1.0
	s_waitcnt lgkmcnt(15)
	v_mfma_f32_16x16x32_bf16 v[40:43], v[134:137], v[28:31], v[40:43]
	v_lshlrev_b64 v[36:37], 11, v[86:87]
	v_lshl_add_u64 v[36:37], v[52:53], 0, v[36:37]
	s_waitcnt lgkmcnt(15)
	v_mfma_f32_16x16x32_bf16 v[40:43], v[138:141], v[24:27], v[40:43]
	v_or_b32_e32 v89, 0xa0, v90
	v_or_b32_e32 v48, s12, v73
	s_waitcnt lgkmcnt(15)
	v_mfma_f32_16x16x32_bf16 v[40:43], v[142:145], v[20:23], v[40:43]
	s_mov_b64 s[10:11], -1
	s_and_b64 vcc, exec, s[24:25]
	s_waitcnt lgkmcnt(15)
	v_mfma_f32_16x16x32_bf16 v[40:43], v[146:149], v[16:19], v[40:43]
	v_sub_u32_e32 v91, v89, v48
	s_nop 6
	v_pk_mul_f32 v[40:41], v[40:41], v[38:39] op_sel_hi:[1,0]
	v_pk_mul_f32 v[42:43], v[42:43], v[38:39] op_sel_hi:[1,0]
	v_cvt_pk_bf16_f32 v40, v40, v41
	s_nop 0
	v_cvt_pk_bf16_f32 v41, v42, v43
	global_store_dwordx2 v[36:37], v[40:41], off
	s_waitcnt lgkmcnt(14)
	v_mfma_f32_16x16x32_bf16 v[40:43], v[150:153], v[32:35], 0
	s_waitcnt lgkmcnt(13)
	v_mfma_f32_16x16x32_bf16 v[40:43], v[154:157], v[28:31], v[40:43]
	s_waitcnt lgkmcnt(12)
	v_mfma_f32_16x16x32_bf16 v[40:43], v[158:161], v[24:27], v[40:43]
	s_waitcnt lgkmcnt(11)
	v_mfma_f32_16x16x32_bf16 v[40:43], v[162:165], v[20:23], v[40:43]
	s_waitcnt lgkmcnt(10)
	v_mfma_f32_16x16x32_bf16 v[40:43], v[166:169], v[16:19], v[40:43]
	s_nop 7
	v_pk_mul_f32 v[40:41], v[38:39], v[40:41] op_sel_hi:[0,1]
	v_pk_mul_f32 v[42:43], v[38:39], v[42:43] op_sel_hi:[0,1]
	v_cvt_pk_bf16_f32 v40, v40, v41
	v_cvt_pk_bf16_f32 v41, v42, v43
	global_store_dwordx2 v[36:37], v[40:41], off offset:32
	s_waitcnt lgkmcnt(9)
	v_mfma_f32_16x16x32_bf16 v[40:43], v[184:187], v[32:35], 0
	s_waitcnt lgkmcnt(8)
	v_mfma_f32_16x16x32_bf16 v[40:43], v[188:191], v[28:31], v[40:43]
	s_waitcnt lgkmcnt(7)
	v_mfma_f32_16x16x32_bf16 v[40:43], v[192:195], v[24:27], v[40:43]
	s_waitcnt lgkmcnt(6)
	v_mfma_f32_16x16x32_bf16 v[40:43], v[196:199], v[20:23], v[40:43]
	s_waitcnt lgkmcnt(5)
	v_mfma_f32_16x16x32_bf16 v[40:43], v[200:203], v[16:19], v[40:43]
	s_nop 7
	v_pk_mul_f32 v[40:41], v[38:39], v[40:41] op_sel_hi:[0,1]
	v_pk_mul_f32 v[42:43], v[38:39], v[42:43] op_sel_hi:[0,1]
	v_cvt_pk_bf16_f32 v40, v40, v41
	v_cvt_pk_bf16_f32 v41, v42, v43
	global_store_dwordx2 v[36:37], v[40:41], off offset:64
	s_waitcnt lgkmcnt(4)
	v_mfma_f32_16x16x32_bf16 v[32:35], v[204:207], v[32:35], 0
	s_waitcnt lgkmcnt(3)
	v_mfma_f32_16x16x32_bf16 v[28:31], v[208:211], v[28:31], v[32:35]
	s_nop 4
	s_waitcnt lgkmcnt(2)
	v_mfma_f32_16x16x32_bf16 v[24:27], v[212:215], v[24:27], v[28:31]
	s_nop 2
	s_waitcnt lgkmcnt(1)
	v_mfma_f32_16x16x32_bf16 v[20:23], v[216:219], v[20:23], v[24:27]
	s_nop 2
	s_waitcnt lgkmcnt(0)
	v_mfma_f32_16x16x32_bf16 v[16:19], v[220:223], v[16:19], v[20:23]
	s_nop 7
	v_pk_mul_f32 v[16:17], v[38:39], v[16:17] op_sel_hi:[0,1]
	v_cvt_pk_bf16_f32 v16, v16, v17
	v_pk_mul_f32 v[18:19], v[38:39], v[18:19] op_sel_hi:[0,1]
	v_cvt_pk_bf16_f32 v17, v18, v19
	global_store_dwordx2 v[36:37], v[16:17], off offset:96
	v_or_b32_e32 v16, s12, v61
	v_mad_u32_u24 v88, v16, s97, v83
	s_cbranch_vccnz .LBB0_567
	ds_read_b128 v[16:19], v88
	ds_read_b128 v[20:23], v88 offset:64
	v_cvt_f32_ubyte0_e32 v176, v91
	v_pk_mul_f32 v[50:51], v[64:65], v[176:177] op_sel_hi:[0,1] neg_lo:[1,0]
	v_add_f32_e32 v87, v64, v50
	v_mov_b32_e32 v86, v50
	v_pk_add_f32 v[92:93], v[78:79], v[50:51] op_sel_hi:[1,0]
	v_pk_add_f32 v[24:25], v[86:87], v[84:85] op_sel_hi:[1,0]
	v_pk_add_f32 v[26:27], v[84:85], v[92:93] op_sel_hi:[0,1]
	v_pk_add_f32 v[128:129], v[86:87], v[70:71] op_sel_hi:[1,0]
	v_pk_add_f32 v[130:131], v[70:71], v[92:93] op_sel_hi:[0,1]
	s_waitcnt vmcnt(11) lgkmcnt(1)
	v_mfma_f32_16x16x32_bf16 v[16:19], v[16:19], v[8:11], v[24:27]
	s_nop 2
	ds_read_b128 v[24:27], v88 offset:2304
	ds_read_b128 v[28:31], v88 offset:2368
	v_cmp_ge_u32_e64 s[26:27], v85, v61
	v_cmp_lt_u32_e32 vcc, v73, v61
	s_waitcnt vmcnt(10) lgkmcnt(2)
	v_mfma_f32_16x16x32_bf16 v[32:35], v[20:23], v[12:15], v[16:19]
	ds_read_b128 v[20:23], v88 offset:4608
	ds_read_b128 v[36:39], v88 offset:4672
	v_pk_add_f32 v[132:133], v[86:87], v[68:69] op_sel_hi:[1,0]
	v_pk_add_f32 v[16:17], v[86:87], v[80:81] op_sel_hi:[1,0]
	v_pk_add_f32 v[18:19], v[80:81], v[92:93] op_sel_hi:[0,1]
	s_nop 2
	v_cndmask_b32_e32 v95, v32, v243, vcc
	v_pk_add_f32 v[134:135], v[68:69], v[92:93] op_sel_hi:[0,1]
	s_waitcnt lgkmcnt(3)
	v_mfma_f32_16x16x32_bf16 v[16:19], v[24:27], v[8:11], v[16:19]
	ds_read_b128 v[24:27], v88 offset:6912
	ds_read_b128 v[40:43], v88 offset:6976
	ds_read_b128 v[44:47], v88 offset:9216
	ds_read_b128 v[96:99], v88 offset:9280
	ds_read_b128 v[100:103], v88 offset:11520
	ds_read_b128 v[104:107], v88 offset:11584
	ds_read_b128 v[108:111], v88 offset:13824
	ds_read_b128 v[112:115], v88 offset:13888
	ds_read_b128 v[116:119], v88 offset:16128
	ds_read_b128 v[120:123], v88 offset:16192
	s_waitcnt lgkmcnt(12)
	v_mfma_f32_16x16x32_bf16 v[16:19], v[28:31], v[12:15], v[16:19]
	v_add_f32_e64 v28, v86, v76
	v_add_f32_e64 v29, v87, v76
	v_pk_add_f32 v[30:31], v[76:77], v[92:93] op_sel_hi:[0,1]
	v_pk_add_f32 v[136:137], v[86:87], v[66:67] op_sel_hi:[1,0]
	v_pk_add_f32 v[138:139], v[66:67], v[92:93] op_sel_hi:[0,1]
	s_waitcnt lgkmcnt(11)
	v_mfma_f32_16x16x32_bf16 v[20:23], v[20:23], v[8:11], v[28:31]
	v_add_f32_e64 v142, v51, v92
	v_add_f32_e64 v143, v51, v93
	s_mov_b64 s[10:11], 0
	v_pk_add_f32 v[28:29], v[86:87], v[74:75] op_sel_hi:[1,0]
	v_pk_add_f32 v[30:31], v[74:75], v[92:93] op_sel_hi:[0,1]
	s_waitcnt lgkmcnt(10)
	v_mfma_f32_16x16x32_bf16 v[20:23], v[36:39], v[12:15], v[20:23]
	ds_read_b128 v[36:39], v88 offset:18432
	ds_read_b128 v[124:127], v88 offset:18496
	s_waitcnt lgkmcnt(11)
	v_mfma_f32_16x16x32_bf16 v[24:27], v[24:27], v[8:11], v[28:31]
	s_nop 2
	v_add_f32_e64 v28, v86, v72
	v_add_f32_e64 v29, v87, v72
	v_pk_add_f32 v[30:31], v[72:73], v[92:93] op_sel_hi:[0,1]
	s_waitcnt lgkmcnt(10)
	v_mfma_f32_16x16x32_bf16 v[24:27], v[40:43], v[12:15], v[24:27]
	v_mov_b32_e32 v86, v51
	v_pk_fma_f32 v[140:141], v[64:65], v[176:177], v[86:87] op_sel_hi:[0,1,1] neg_lo:[1,0,0]
	s_waitcnt lgkmcnt(9)
	v_mfma_f32_16x16x32_bf16 v[28:31], v[44:47], v[8:11], v[28:31]
	s_waitcnt lgkmcnt(7)
	v_mfma_f32_16x16x32_bf16 v[40:43], v[100:103], v[8:11], v[128:131]
	v_mfma_f32_16x16x32_bf16 v[28:31], v[96:99], v[12:15], v[28:31]
	v_cndmask_b32_e64 v96, v243, v33, s[26:27]
	v_cmp_ge_u32_e64 s[26:27], v77, v61
	v_max3_f32 v44, v67, v95, v96
	s_waitcnt lgkmcnt(1)
	v_mfma_f32_16x16x32_bf16 v[36:39], v[36:39], v[8:11], v[140:143]
	v_cndmask_b32_e64 v98, v243, v34, s[26:27]
	v_cmp_ge_u32_e64 s[26:27], v75, v61
	s_waitcnt lgkmcnt(0)
	v_mfma_f32_16x16x32_bf16 v[100:103], v[124:127], v[12:15], v[36:39]
	v_cndmask_b32_e64 v97, v243, v35, s[26:27]
	v_cmp_le_u32_e64 s[26:27], v73, v61
	v_mfma_f32_16x16x32_bf16 v[32:35], v[104:107], v[12:15], v[40:43]
	s_nop 2
	v_max3_f32 v40, v44, v98, v97
	v_max3_f32 v44, v40, v16, v17
	v_max3_f32 v44, v44, v18, v19
	v_max3_f32 v44, v44, v20, v21
	v_mfma_f32_16x16x32_bf16 v[40:43], v[108:111], v[8:11], v[132:135]
	v_max3_f32 v44, v44, v22, v23
	v_max3_f32 v44, v44, v24, v25
	v_max3_f32 v49, v44, v26, v27
	v_mfma_f32_16x16x32_bf16 v[44:47], v[116:119], v[8:11], v[136:139]
	v_max3_f32 v49, v49, v28, v29
	v_max3_f32 v49, v49, v30, v31
	v_max3_f32 v49, v49, v32, v33
	v_mfma_f32_16x16x32_bf16 v[40:43], v[112:115], v[12:15], v[40:43]
	v_max3_f32 v49, v49, v34, v35
	v_cndmask_b32_e32 v36, v243, v101, vcc
	v_cmp_le_u32_e32 vcc, v77, v61
	v_mfma_f32_16x16x32_bf16 v[44:47], v[120:123], v[12:15], v[44:47]
	v_cndmask_b32_e64 v37, v243, v100, s[26:27]
	s_nop 2
	v_max3_f32 v49, v49, v40, v41
	v_max3_f32 v49, v49, v42, v43
	v_cndmask_b32_e32 v83, v243, v102, vcc
	v_cmp_le_u32_e32 vcc, v75, v61
	v_max3_f32 v49, v49, v44, v45
	v_max3_f32 v49, v49, v46, v47
	v_max3_f32 v38, v49, v37, v36
	v_cndmask_b32_e32 v39, v243, v103, vcc
	v_max3_f32 v99, v38, v83, v39

.LBB0_571:
	ds_bpermute_b32 v25, v69, v24
	v_sub_f32_e32 v8, v67, v8
	v_exp_f32_e32 v8, v8
	v_mov_b32_e32 v83, v63
	s_waitcnt lgkmcnt(0)
	v_add_f32_e32 v24, v24, v25
	ds_bpermute_b32 v25, v71, v24
	s_waitcnt lgkmcnt(0)
	ds_read2_b64 v[130:133], v55 offset0:8 offset1:12
	ds_read2_b64 v[134:137], v55 offset0:16 offset1:20
	ds_read2_b64 v[138:141], v55 offset0:24 offset1:28
	ds_read2_b64 v[142:145], v55 offset0:32 offset1:36
	ds_read2_b64 v[146:149], v55 offset0:40 offset1:44
	ds_read2_b64 v[150:153], v56 offset0:40 offset1:44
	ds_read2_b64 v[154:157], v56 offset0:48 offset1:52
	ds_read2_b64 v[158:161], v56 offset0:56 offset1:60
	ds_read2_b64 v[162:165], v56 offset0:64 offset1:68
	ds_read2_b64 v[166:169], v56 offset0:72 offset1:76
	ds_read2_b64 v[184:187], v57 offset0:72 offset1:76
	ds_read2_b64 v[188:191], v57 offset0:80 offset1:84
	ds_read2_b64 v[192:195], v57 offset0:88 offset1:92
	ds_read2_b64 v[196:199], v57 offset0:96 offset1:100
	ds_read2_b64 v[200:203], v57 offset0:104 offset1:108
	ds_read2_b64 v[204:207], v58 offset0:104 offset1:108
	ds_read2_b64 v[208:211], v58 offset0:112 offset1:116
	ds_read2_b64 v[212:215], v58 offset0:120 offset1:124
	ds_read2_b64 v[216:219], v58 offset0:128 offset1:132
	ds_read2_b64 v[220:223], v58 offset0:136 offset1:140
	v_add_f32_e32 v24, v24, v25
	v_add_f32_e32 v95, v8, v24
	v_cvt_pk_bf16_f32 v8, v17, v91
	v_cvt_pk_bf16_f32 v9, v9, v89
	v_cvt_pk_bf16_f32 v10, v10, v11
	v_cvt_pk_bf16_f32 v11, v13, v14
	v_cvt_pk_bf16_f32 v24, v12, v15
	v_cvt_pk_bf16_f32 v25, v16, v18
	v_cvt_pk_bf16_f32 v26, v19, v21
	v_cvt_pk_bf16_f32 v27, v22, v23
	v_cvt_pk_bf16_f32 v20, v20, v28
	v_div_scale_f32 v28, s[10:11], v95, v95, 1.0
	v_cvt_pk_bf16_f32 v21, v29, v30
	v_rcp_f32_e32 v29, v28
	v_cvt_pk_bf16_f32 v22, v31, v33
	v_cvt_pk_bf16_f32 v23, v34, v35
	v_cvt_pk_bf16_f32 v16, v32, v40
	v_cvt_pk_bf16_f32 v17, v41, v42
	v_cvt_pk_bf16_f32 v18, v43, v44
	s_nop 0
	v_fma_f32 v30, -v28, v29, 1.0
	v_fmac_f32_e32 v29, v30, v29
	v_div_scale_f32 v30, vcc, 1.0, v95, 1.0
	v_mul_f32_e32 v31, v30, v29
	v_fma_f32 v32, -v28, v31, v30
	v_cvt_pk_bf16_f32 v19, v45, v46
	v_cvt_pk_bf16_f32 v12, v37, v36
	v_cvt_pk_bf16_f32 v13, v47, v39
	v_cvt_pk_bf16_f32 v14, v38, v92
	v_cvt_pk_bf16_f32 v15, v94, v93
	v_fmac_f32_e32 v31, v32, v29
	s_waitcnt lgkmcnt(15)
	v_mfma_f32_16x16x32_bf16 v[32:35], v[130:133], v[8:11], 0
	v_fma_f32 v28, -v28, v31, v30
	v_div_fmas_f32 v28, v28, v29, v31
	v_div_fixup_f32 v30, v28, v95, 1.0
	s_waitcnt lgkmcnt(15)
	v_mfma_f32_16x16x32_bf16 v[32:35], v[134:137], v[24:27], v[32:35]
	v_lshlrev_b64 v[28:29], 11, v[82:83]
	v_lshl_add_u64 v[28:29], v[52:53], 0, v[28:29]
	s_waitcnt lgkmcnt(15)
	v_mfma_f32_16x16x32_bf16 v[32:35], v[138:141], v[20:23], v[32:35]
	s_mov_b64 s[10:11], -1
	s_and_b64 vcc, exec, s[24:25]
	s_waitcnt lgkmcnt(15)
	v_mfma_f32_16x16x32_bf16 v[32:35], v[142:145], v[16:19], v[32:35]
	s_waitcnt lgkmcnt(15)
	v_mfma_f32_16x16x32_bf16 v[32:35], v[146:149], v[12:15], v[32:35]
	s_nop 7
	v_pk_mul_f32 v[32:33], v[30:31], v[32:33] op_sel_hi:[0,1]
	v_pk_mul_f32 v[34:35], v[30:31], v[34:35] op_sel_hi:[0,1]
	v_cvt_pk_bf16_f32 v32, v32, v33
	v_cvt_pk_bf16_f32 v33, v34, v35
	global_store_dwordx2 v[28:29], v[32:33], off
	s_waitcnt lgkmcnt(14)
	v_mfma_f32_16x16x32_bf16 v[32:35], v[150:153], v[8:11], 0
	s_waitcnt lgkmcnt(13)
	v_mfma_f32_16x16x32_bf16 v[32:35], v[154:157], v[24:27], v[32:35]
	s_waitcnt lgkmcnt(12)
	v_mfma_f32_16x16x32_bf16 v[32:35], v[158:161], v[20:23], v[32:35]
	s_waitcnt lgkmcnt(11)
	v_mfma_f32_16x16x32_bf16 v[32:35], v[162:165], v[16:19], v[32:35]
	s_waitcnt lgkmcnt(10)
	v_mfma_f32_16x16x32_bf16 v[32:35], v[166:169], v[12:15], v[32:35]
	s_nop 7
	v_pk_mul_f32 v[32:33], v[30:31], v[32:33] op_sel_hi:[0,1]
	v_pk_mul_f32 v[34:35], v[30:31], v[34:35] op_sel_hi:[0,1]
	v_cvt_pk_bf16_f32 v32, v32, v33
	v_cvt_pk_bf16_f32 v33, v34, v35
	global_store_dwordx2 v[28:29], v[32:33], off offset:32
	s_waitcnt lgkmcnt(9)
	v_mfma_f32_16x16x32_bf16 v[32:35], v[184:187], v[8:11], 0
	s_waitcnt lgkmcnt(8)
	v_mfma_f32_16x16x32_bf16 v[32:35], v[188:191], v[24:27], v[32:35]
	s_waitcnt lgkmcnt(7)
	v_mfma_f32_16x16x32_bf16 v[32:35], v[192:195], v[20:23], v[32:35]
	s_waitcnt lgkmcnt(6)
	v_mfma_f32_16x16x32_bf16 v[32:35], v[196:199], v[16:19], v[32:35]
	s_waitcnt lgkmcnt(5)
	v_mfma_f32_16x16x32_bf16 v[32:35], v[200:203], v[12:15], v[32:35]
	v_or_b32_e32 v36, 0xb0, v90
	v_sub_u32_e32 v38, v36, v48
	s_nop 5
	v_pk_mul_f32 v[32:33], v[30:31], v[32:33] op_sel_hi:[0,1]
	v_pk_mul_f32 v[34:35], v[30:31], v[34:35] op_sel_hi:[0,1]
	v_cvt_pk_bf16_f32 v32, v32, v33
	v_cvt_pk_bf16_f32 v33, v34, v35
	global_store_dwordx2 v[28:29], v[32:33], off offset:64
	s_waitcnt lgkmcnt(4)
	v_mfma_f32_16x16x32_bf16 v[8:11], v[204:207], v[8:11], 0
	s_waitcnt lgkmcnt(3)
	v_mfma_f32_16x16x32_bf16 v[8:11], v[208:211], v[24:27], v[8:11]
	s_waitcnt lgkmcnt(2)
	v_mfma_f32_16x16x32_bf16 v[8:11], v[212:215], v[20:23], v[8:11]
	s_waitcnt lgkmcnt(1)
	v_mfma_f32_16x16x32_bf16 v[8:11], v[216:219], v[16:19], v[8:11]
	s_waitcnt lgkmcnt(0)
	v_mfma_f32_16x16x32_bf16 v[8:11], v[220:223], v[12:15], v[8:11]
	s_nop 7
	v_pk_mul_f32 v[8:9], v[30:31], v[8:9] op_sel_hi:[0,1]
	v_pk_mul_f32 v[10:11], v[30:31], v[10:11] op_sel_hi:[0,1]
	v_cvt_pk_bf16_f32 v8, v8, v9
	v_cvt_pk_bf16_f32 v9, v10, v11
	global_store_dwordx2 v[28:29], v[8:9], off offset:96
	s_cbranch_vccnz .LBB0_573
	ds_read_b128 v[8:11], v88 offset:2304
	ds_read_b128 v[12:15], v88 offset:2368
	v_cvt_f32_ubyte0_e32 v178, v38
	v_pk_mul_f32 v[82:83], v[64:65], v[178:179] op_sel_hi:[0,1] neg_lo:[1,0]
	v_add_f32_e32 v125, v64, v82
	v_mov_b32_e32 v124, v82
	v_pk_add_f32 v[78:79], v[78:79], v[82:83] op_sel_hi:[1,0]
	v_pk_add_f32 v[16:17], v[124:125], v[80:81] op_sel_hi:[1,0]
	v_pk_add_f32 v[18:19], v[80:81], v[78:79] op_sel_hi:[0,1]
	v_cmp_ge_u32_e64 s[24:25], v85, v61
	v_cmp_lt_u32_e32 vcc, v73, v61
	s_waitcnt vmcnt(13) lgkmcnt(1)
	v_mfma_f32_16x16x32_bf16 v[8:11], v[8:11], v[0:3], v[16:19]
	s_nop 2
	ds_read_b128 v[16:19], v88 offset:4608
	ds_read_b128 v[20:23], v88 offset:4672
	v_pk_add_f32 v[122:123], v[124:125], v[66:67] op_sel_hi:[1,0]
	s_mov_b64 s[10:11], 0
	s_waitcnt vmcnt(12) lgkmcnt(2)
	v_mfma_f32_16x16x32_bf16 v[24:27], v[12:15], v[4:7], v[8:11]
	ds_read_b128 v[12:15], v88 offset:6912
	ds_read_b128 v[28:31], v88 offset:6976
	s_nop 0
	v_pk_add_f32 v[8:9], v[124:125], v[76:77] op_sel_hi:[1,0]
	v_pk_add_f32 v[10:11], v[76:77], v[78:79] op_sel_hi:[0,1]
	s_nop 2
	v_cndmask_b32_e32 v37, v24, v243, vcc
	s_waitcnt lgkmcnt(3)
	v_mfma_f32_16x16x32_bf16 v[8:11], v[16:19], v[0:3], v[8:11]
	ds_read_b128 v[16:19], v88 offset:9216
	ds_read_b128 v[32:35], v88 offset:9280
	ds_read_b128 v[40:43], v88 offset:11520
	ds_read_b128 v[44:47], v88 offset:11584
	ds_read_b128 v[90:93], v88 offset:13824
	ds_read_b128 v[94:97], v88 offset:13888
	ds_read_b128 v[98:101], v88 offset:16128
	ds_read_b128 v[102:105], v88 offset:16192
	ds_read_b128 v[106:109], v88 offset:18432
	ds_read_b128 v[110:113], v88 offset:18496
	s_waitcnt lgkmcnt(12)
	v_mfma_f32_16x16x32_bf16 v[8:11], v[20:23], v[4:7], v[8:11]
	v_add_f32_e64 v20, v124, v74
	v_add_f32_e64 v21, v125, v74
	v_pk_add_f32 v[22:23], v[74:75], v[78:79] op_sel_hi:[0,1]
	ds_read_b128 v[114:117], v88 offset:20736
	ds_read_b128 v[118:121], v88 offset:20800
	s_waitcnt lgkmcnt(13)
	v_mfma_f32_16x16x32_bf16 v[12:15], v[12:15], v[0:3], v[20:23]
	s_nop 2
	v_add_f32_e64 v20, v124, v72
	v_add_f32_e64 v21, v125, v72
	v_pk_add_f32 v[22:23], v[72:73], v[78:79] op_sel_hi:[0,1]
	s_waitcnt lgkmcnt(12)
	v_mfma_f32_16x16x32_bf16 v[12:15], v[28:31], v[4:7], v[12:15]
	v_add_f32_e64 v28, v124, v68
	v_add_f32_e64 v29, v125, v68
	v_pk_add_f32 v[30:31], v[68:69], v[78:79] op_sel_hi:[0,1]
	s_waitcnt lgkmcnt(11)
	v_mfma_f32_16x16x32_bf16 v[16:19], v[16:19], v[0:3], v[20:23]
	s_nop 2
	v_add_f32_e64 v20, v124, v70
	v_add_f32_e64 v21, v125, v70
	v_pk_add_f32 v[22:23], v[70:71], v[78:79] op_sel_hi:[0,1]
	s_waitcnt lgkmcnt(7)
	v_mfma_f32_16x16x32_bf16 v[28:31], v[90:93], v[0:3], v[28:31]
	v_mfma_f32_16x16x32_bf16 v[20:23], v[40:43], v[0:3], v[20:23]
	v_add_f32_e64 v42, v83, v78
	v_add_f32_e64 v43, v83, v79
	v_mfma_f32_16x16x32_bf16 v[20:23], v[44:47], v[4:7], v[20:23]
	v_cndmask_b32_e64 v45, v243, v25, s[24:25]
	v_cmp_ge_u32_e64 s[24:25], v77, v61
	v_mfma_f32_16x16x32_bf16 v[16:19], v[32:35], v[4:7], v[16:19]
	s_nop 0
	v_cndmask_b32_e64 v47, v243, v26, s[24:25]
	v_cmp_ge_u32_e64 s[24:25], v75, v61
	v_max3_f32 v34, v67, v37, v45
	v_pk_add_f32 v[32:33], v[124:125], v[54:55] op_sel_hi:[1,0]
	v_cndmask_b32_e64 v46, v243, v27, s[24:25]
	s_waitcnt lgkmcnt(6)
	v_mfma_f32_16x16x32_bf16 v[24:27], v[94:97], v[4:7], v[28:31]
	v_mov_b32_e32 v124, v83
	v_pk_fma_f32 v[40:41], v[64:65], v[178:179], v[124:125] op_sel_hi:[0,1,1] neg_lo:[1,0,0]
	v_pk_add_f32 v[124:125], v[66:67], v[78:79] op_sel_hi:[0,1]
	v_max3_f32 v28, v34, v47, v46
	v_max3_f32 v34, v28, v8, v9
	v_max3_f32 v34, v34, v10, v11
	v_max3_f32 v34, v34, v12, v13
	v_max3_f32 v34, v34, v14, v15
	s_waitcnt lgkmcnt(5)
	v_mfma_f32_16x16x32_bf16 v[28:31], v[98:101], v[0:3], v[122:125]
	v_max3_f32 v34, v34, v16, v17
	v_max3_f32 v39, v34, v18, v19
	v_pk_add_f32 v[34:35], v[54:55], v[78:79] op_sel_hi:[0,1]
	s_waitcnt lgkmcnt(1)
	v_mfma_f32_16x16x32_bf16 v[40:43], v[114:117], v[0:3], v[40:43]
	v_max3_f32 v39, v39, v20, v21
	v_max3_f32 v39, v39, v22, v23
	v_max3_f32 v39, v39, v24, v25
	v_mfma_f32_16x16x32_bf16 v[32:35], v[106:109], v[0:3], v[32:35]
	v_max3_f32 v39, v39, v26, v27
	v_cmp_le_u32_e64 s[24:25], v73, v61
	v_mfma_f32_16x16x32_bf16 v[28:31], v[102:105], v[4:7], v[28:31]
	v_mfma_f32_16x16x32_bf16 v[32:35], v[110:113], v[4:7], v[32:35]
	s_waitcnt lgkmcnt(0)
	v_mfma_f32_16x16x32_bf16 v[90:93], v[118:121], v[4:7], v[40:43]
	s_nop 4
	v_max3_f32 v39, v39, v28, v29
	v_max3_f32 v39, v39, v30, v31
	v_max3_f32 v39, v39, v32, v33
	v_max3_f32 v39, v39, v34, v35
	v_cndmask_b32_e32 v40, v243, v91, vcc
	v_cmp_le_u32_e32 vcc, v77, v61
	v_cndmask_b32_e64 v41, v243, v90, s[24:25]
	v_max3_f32 v39, v39, v41, v40
	v_cndmask_b32_e32 v43, v243, v92, vcc
	v_cmp_le_u32_e32 vcc, v75, v61
	s_nop 1
	v_cndmask_b32_e32 v42, v243, v93, vcc
	v_max3_f32 v82, v39, v43, v42

.LBB0_577:
	v_sub_f32_e32 v1, v37, v0
	v_exp_f32_e32 v1, v1
	v_sub_f32_e32 v3, v45, v0
	v_exp_f32_e32 v3, v3
	s_waitcnt vmcnt(12)
	v_sub_f32_e32 v4, v47, v0
	v_exp_f32_e32 v4, v4
	v_sub_f32_e32 v5, v46, v0
	v_exp_f32_e32 v5, v5
	v_sub_f32_e32 v6, v8, v0
	v_add_f32_e32 v2, v1, v39
	v_exp_f32_e32 v6, v6
	v_sub_f32_e32 v7, v9, v0
	v_add_f32_e32 v2, v3, v2
	v_exp_f32_e32 v7, v7
	v_sub_f32_e32 v8, v10, v0
	v_add_f32_e32 v2, v4, v2
	v_exp_f32_e32 v8, v8
	v_sub_f32_e32 v9, v11, v0
	v_add_f32_e32 v2, v5, v2
	v_exp_f32_e32 v9, v9
	v_sub_f32_e32 v10, v12, v0
	v_add_f32_e32 v2, v6, v2
	v_exp_f32_e32 v10, v10
	v_sub_f32_e32 v11, v13, v0
	v_add_f32_e32 v2, v7, v2
	v_exp_f32_e32 v11, v11
	v_sub_f32_e32 v12, v14, v0
	v_add_f32_e32 v2, v8, v2
	v_exp_f32_e32 v36, v12
	v_sub_f32_e32 v12, v15, v0
	v_add_f32_e32 v2, v9, v2
	v_exp_f32_e32 v15, v12
	v_sub_f32_e32 v12, v16, v0
	v_add_f32_e32 v2, v10, v2
	v_exp_f32_e32 v37, v12
	v_sub_f32_e32 v12, v17, v0
	v_add_f32_e32 v2, v11, v2
	v_exp_f32_e32 v38, v12
	v_sub_f32_e32 v12, v18, v0
	v_add_f32_e32 v2, v36, v2
	v_exp_f32_e32 v39, v12
	v_sub_f32_e32 v12, v19, v0
	v_add_f32_e32 v2, v15, v2
	v_exp_f32_e32 v45, v12
	v_sub_f32_e32 v12, v20, v0
	v_add_f32_e32 v2, v37, v2
	v_exp_f32_e32 v20, v12
	v_sub_f32_e32 v12, v21, v0
	v_add_f32_e32 v2, v38, v2
	v_exp_f32_e32 v21, v12
	v_sub_f32_e32 v12, v22, v0
	v_add_f32_e32 v2, v39, v2
	v_exp_f32_e32 v22, v12
	v_sub_f32_e32 v12, v23, v0
	v_add_f32_e32 v2, v45, v2
	v_exp_f32_e32 v23, v12
	v_sub_f32_e32 v12, v24, v0
	v_add_f32_e32 v2, v20, v2
	v_exp_f32_e32 v24, v12
	v_sub_f32_e32 v12, v25, v0
	v_add_f32_e32 v2, v21, v2
	v_exp_f32_e32 v25, v12
	v_sub_f32_e32 v12, v26, v0
	v_add_f32_e32 v2, v22, v2
	v_exp_f32_e32 v26, v12
	v_sub_f32_e32 v12, v27, v0
	v_add_f32_e32 v2, v23, v2
	v_exp_f32_e32 v27, v12
	v_sub_f32_e32 v12, v28, v0
	v_add_f32_e32 v2, v24, v2
	v_exp_f32_e32 v28, v12
	v_sub_f32_e32 v12, v29, v0
	v_add_f32_e32 v2, v25, v2
	v_exp_f32_e32 v29, v12
	v_sub_f32_e32 v12, v30, v0
	v_add_f32_e32 v2, v26, v2
	v_exp_f32_e32 v30, v12
	v_sub_f32_e32 v12, v31, v0
	v_add_f32_e32 v2, v27, v2
	v_exp_f32_e32 v31, v12
	v_sub_f32_e32 v12, v32, v0
	v_add_f32_e32 v2, v28, v2
	v_exp_f32_e32 v32, v12
	v_sub_f32_e32 v12, v33, v0
	v_add_f32_e32 v2, v29, v2
	v_exp_f32_e32 v33, v12
	v_sub_f32_e32 v12, v34, v0
	v_add_f32_e32 v2, v30, v2
	v_exp_f32_e32 v34, v12
	v_sub_f32_e32 v12, v35, v0
	v_add_f32_e32 v2, v31, v2
	v_exp_f32_e32 v35, v12
	v_sub_f32_e32 v12, v41, v0
	v_add_f32_e32 v2, v32, v2
	v_exp_f32_e32 v41, v12
	v_sub_f32_e32 v12, v40, v0
	v_add_f32_e32 v2, v33, v2
	v_exp_f32_e32 v40, v12
	v_sub_f32_e32 v12, v43, v0
	v_add_f32_e32 v2, v34, v2
	v_exp_f32_e32 v43, v12
	v_sub_f32_e32 v12, v42, v0
	v_add_f32_e32 v2, v35, v2
	v_exp_f32_e32 v42, v12
	v_add_f32_e32 v2, v41, v2
	v_add_f32_e32 v2, v40, v2
	v_add_f32_e32 v2, v43, v2
	v_add_f32_e32 v2, v42, v2
	ds_bpermute_b32 v12, v69, v2
	v_sub_f32_e32 v0, v67, v0
	v_exp_f32_e32 v0, v0
	v_cvt_pk_bf16_f32 v16, v44, v44
	v_cvt_pk_bf16_f32 v17, v44, v44
	s_waitcnt lgkmcnt(0)
	v_add_f32_e32 v2, v2, v12
	ds_bpermute_b32 v12, v71, v2
	v_cvt_pk_bf16_f32 v18, v1, v3
	v_cvt_pk_bf16_f32 v19, v4, v5
	v_mov_b32_e32 v61, v63
	s_waitcnt lgkmcnt(0)
	ds_read2_b64 v[130:133], v55 offset0:8 offset1:12
	ds_read2_b64 v[134:137], v55 offset0:16 offset1:20
	ds_read2_b64 v[138:141], v55 offset0:24 offset1:28
	ds_read2_b64 v[142:145], v55 offset0:32 offset1:36
	ds_read2_b64 v[146:149], v55 offset0:40 offset1:44
	ds_read2_b64 v[150:153], v56 offset0:40 offset1:44
	ds_read2_b64 v[154:157], v56 offset0:48 offset1:52
	ds_read2_b64 v[158:161], v56 offset0:56 offset1:60
	ds_read2_b64 v[162:165], v56 offset0:64 offset1:68
	ds_read2_b64 v[166:169], v56 offset0:72 offset1:76
	ds_read2_b64 v[184:187], v57 offset0:72 offset1:76
	ds_read2_b64 v[188:191], v57 offset0:80 offset1:84
	ds_read2_b64 v[192:195], v57 offset0:88 offset1:92
	ds_read2_b64 v[196:199], v57 offset0:96 offset1:100
	ds_read2_b64 v[200:203], v57 offset0:104 offset1:108
	ds_read2_b64 v[204:207], v58 offset0:104 offset1:108
	ds_read2_b64 v[208:211], v58 offset0:112 offset1:116
	ds_read2_b64 v[212:215], v58 offset0:120 offset1:124
	ds_read2_b64 v[216:219], v58 offset0:128 offset1:132
	ds_read2_b64 v[220:223], v58 offset0:136 offset1:140
	v_add_f32_e32 v2, v2, v12
	v_add_f32_e32 v46, v0, v2
	v_cvt_pk_bf16_f32 v12, v6, v7
	v_cvt_pk_bf16_f32 v13, v8, v9
	v_cvt_pk_bf16_f32 v14, v10, v11
	v_cvt_pk_bf16_f32 v15, v36, v15
	v_cvt_pk_bf16_f32 v8, v37, v38
	v_cvt_pk_bf16_f32 v9, v39, v45
	v_cvt_pk_bf16_f32 v10, v20, v21
	v_div_scale_f32 v20, s[10:11], v46, v46, 1.0
	v_rcp_f32_e32 v21, v20
	v_cvt_pk_bf16_f32 v11, v22, v23
	v_cvt_pk_bf16_f32 v4, v24, v25
	v_cvt_pk_bf16_f32 v5, v26, v27
	v_cvt_pk_bf16_f32 v6, v28, v29
	v_cvt_pk_bf16_f32 v7, v30, v31
	s_nop 0
	v_fma_f32 v22, -v20, v21, 1.0
	v_fmac_f32_e32 v21, v22, v21
	v_div_scale_f32 v22, vcc, 1.0, v46, 1.0
	v_mul_f32_e32 v23, v22, v21
	v_fma_f32 v24, -v20, v23, v22
	v_cvt_pk_bf16_f32 v0, v32, v33
	v_cvt_pk_bf16_f32 v1, v34, v35
	v_cvt_pk_bf16_f32 v2, v41, v40
	v_cvt_pk_bf16_f32 v3, v43, v42
	v_fmac_f32_e32 v23, v24, v21
	s_waitcnt lgkmcnt(15)
	v_mfma_f32_16x16x32_bf16 v[24:27], v[130:133], v[16:19], 0
	v_fma_f32 v20, -v20, v23, v22
	v_div_fmas_f32 v20, v20, v21, v23
	v_div_fixup_f32 v22, v20, v46, 1.0
	s_waitcnt lgkmcnt(15)
	v_mfma_f32_16x16x32_bf16 v[24:27], v[134:137], v[12:15], v[24:27]
	v_lshlrev_b64 v[20:21], 11, v[60:61]
	v_lshl_add_u64 v[20:21], v[52:53], 0, v[20:21]
	s_waitcnt lgkmcnt(15)
	v_mfma_f32_16x16x32_bf16 v[24:27], v[138:141], v[8:11], v[24:27]
	s_waitcnt lgkmcnt(15)
	v_mfma_f32_16x16x32_bf16 v[24:27], v[142:145], v[4:7], v[24:27]
	s_waitcnt lgkmcnt(15)
	v_mfma_f32_16x16x32_bf16 v[24:27], v[146:149], v[0:3], v[24:27]
	s_nop 7
	v_pk_mul_f32 v[24:25], v[24:25], v[22:23] op_sel_hi:[1,0]
	v_pk_mul_f32 v[26:27], v[26:27], v[22:23] op_sel_hi:[1,0]
	v_cvt_pk_bf16_f32 v24, v24, v25
	s_nop 0
	v_cvt_pk_bf16_f32 v25, v26, v27
	global_store_dwordx2 v[20:21], v[24:25], off
	s_waitcnt lgkmcnt(14)
	v_mfma_f32_16x16x32_bf16 v[24:27], v[150:153], v[16:19], 0
	s_waitcnt lgkmcnt(13)
	v_mfma_f32_16x16x32_bf16 v[24:27], v[154:157], v[12:15], v[24:27]
	s_waitcnt lgkmcnt(12)
	v_mfma_f32_16x16x32_bf16 v[24:27], v[158:161], v[8:11], v[24:27]
	s_waitcnt lgkmcnt(11)
	v_mfma_f32_16x16x32_bf16 v[24:27], v[162:165], v[4:7], v[24:27]
	s_waitcnt lgkmcnt(10)
	v_mfma_f32_16x16x32_bf16 v[24:27], v[166:169], v[0:3], v[24:27]
	s_nop 7
	v_pk_mul_f32 v[24:25], v[22:23], v[24:25] op_sel_hi:[0,1]
	v_pk_mul_f32 v[26:27], v[22:23], v[26:27] op_sel_hi:[0,1]
	v_cvt_pk_bf16_f32 v24, v24, v25
	v_cvt_pk_bf16_f32 v25, v26, v27
	global_store_dwordx2 v[20:21], v[24:25], off offset:32
	s_waitcnt lgkmcnt(9)
	v_mfma_f32_16x16x32_bf16 v[24:27], v[184:187], v[16:19], 0
	s_waitcnt lgkmcnt(8)
	v_mfma_f32_16x16x32_bf16 v[24:27], v[188:191], v[12:15], v[24:27]
	s_waitcnt lgkmcnt(7)
	v_mfma_f32_16x16x32_bf16 v[24:27], v[192:195], v[8:11], v[24:27]
	s_waitcnt lgkmcnt(6)
	v_mfma_f32_16x16x32_bf16 v[24:27], v[196:199], v[4:7], v[24:27]
	s_waitcnt lgkmcnt(5)
	v_mfma_f32_16x16x32_bf16 v[24:27], v[200:203], v[0:3], v[24:27]
	s_nop 7
	v_pk_mul_f32 v[24:25], v[22:23], v[24:25] op_sel_hi:[0,1]
	v_pk_mul_f32 v[26:27], v[22:23], v[26:27] op_sel_hi:[0,1]
	v_cvt_pk_bf16_f32 v24, v24, v25
	v_cvt_pk_bf16_f32 v25, v26, v27
	global_store_dwordx2 v[20:21], v[24:25], off offset:64
	s_waitcnt lgkmcnt(4)
	v_mfma_f32_16x16x32_bf16 v[16:19], v[204:207], v[16:19], 0
	s_waitcnt lgkmcnt(3)
	v_mfma_f32_16x16x32_bf16 v[12:15], v[208:211], v[12:15], v[16:19]
	s_nop 4
	s_waitcnt lgkmcnt(2)
	v_mfma_f32_16x16x32_bf16 v[8:11], v[212:215], v[8:11], v[12:15]
	s_nop 2
	s_waitcnt lgkmcnt(1)
	v_mfma_f32_16x16x32_bf16 v[4:7], v[216:219], v[4:7], v[8:11]
	s_nop 2
	s_waitcnt lgkmcnt(0)
	v_mfma_f32_16x16x32_bf16 v[0:3], v[220:223], v[0:3], v[4:7]
	s_nop 7
	v_pk_mul_f32 v[0:1], v[22:23], v[0:1] op_sel_hi:[0,1]
	v_pk_mul_f32 v[2:3], v[22:23], v[2:3] op_sel_hi:[0,1]
	v_cvt_pk_bf16_f32 v0, v0, v1
	v_cvt_pk_bf16_f32 v1, v2, v3
	global_store_dwordx2 v[20:21], v[0:1], off offset:96
	s_barrier
	s_addk_i32 s81, 0x100
	s_branch .Lq_remap
